# combo28: combo23 + pass C issues the eight g_o staging loads at the unit head (with the v-row loads) instead of after the intra-chunk MFMAs: one memory latency off each unit's dependent chain
# speedup vs baseline: 1.0054x; 1.0054x over previous
; #define LAS __attribute__((address_space(3)))
; __device__ __forceinline__ int crow(int r, int hi) { return (r & 3) + 8 * (r >> 2) + 4 * hi; }
; __device__ __forceinline__ float bf2f(unsigned short v) { return __uint_as_float((unsigned)v << 16); }
; __device__ __forceinline__ unsigned f2bf(float f) { return pk2(f, 0.f) & 0xffffu; }
; __device__ __forceinline__ int crow(int r, int hi) { return (r & 3) + 8 * (r >> 2) + 4 * hi; }
; __device__ __forceinline__ void gla_pass_c(LAS unsigned char* ldsl, const bf16_t* __restrict__ proj, const float* __restrict__ Btab, const float* __restrict__ Gst, const float* __restrict__ gout, bf16_t* __restrict__ mixed) {
;     ...
;         { const bf16_t* gp = proj + (row0 + 32 * tb + crw) * NIN + 1024 + h * 128 + ccl * 8; u32x4 sv[8];
; #pragma unroll
;           for (int i = 0; i < 8; ++i) sv[i] = *(const u32x4*)(gp + (size_t)(4 * i) * NIN);
; #pragma unroll
;           for (int i = 0; i < 8; ++i) *(LAS u32x4*)(Lw + (4 * i + crw) * 256 + ccl * 16) = sv[i]; }
;         float gn[4];
; #pragma unroll
;         for (int dvb = 0; dvb < 4; ++dvb) gn[dvb] = gout[32 * dvb + r];
; #pragma unroll
;         for (int i = 0; i < 16; ++i) { const int tr = crow(i, hh);
;             const float tot = half_sum32((o[0][i] * o[0][i] + o[1][i] * o[1][i]) + (o[2][i] * o[2][i] + o[3][i] * o[3][i]));
;             const float rr = __builtin_amdgcn_rsqf(tot * (1.0f / 128.0f) + EPS);
; #pragma unroll
;             for (int dvb = 0; dvb < 4; ++dvb) { const float g = bf2f(Lh[tr * 128 + 32 * dvb + r]);
;                 const float val = o[dvb][i] * rr * gn[dvb] * (g * __builtin_amdgcn_rcpf(1.0f + __expf(-g)));
;                 Lh[(32 + tr) * 128 + 32 * dvb + r] = (bf16_t)f2bf(val); } }
.LBB0_873:
	v_or3_b32 v122, s2, v110, v122
	v_lshlrev_b64 v[64:65], 12, v[122:123]
	v_lshl_add_u64 v[64:65], s[60:61], 0, v[64:65]
	v_lshlrev_b32_e32 v160, 1, v124
	v_lshl_add_u64 v[64:65], v[64:65], 0, v[160:161]
	v_mov_b32_e32 v121, v161
	v_lshl_add_u64 v[92:93], v[64:65], 0, v[120:121]
	v_add_co_u32_e32 v68, vcc, 0x4000, v92
	s_nop 0
	v_addc_co_u32_e32 v69, vcc, 0, v93, vcc
	v_add_co_u32_e32 v72, vcc, 0x8000, v92
	s_nop 0
	v_addc_co_u32_e32 v73, vcc, 0, v93, vcc
	v_add_co_u32_e32 v76, vcc, 0xc000, v92
	s_nop 0
	v_addc_co_u32_e32 v77, vcc, 0, v93, vcc
	v_add_co_u32_e32 v80, vcc, s51, v92
	s_mov_b32 s33, 0x18000
	s_nop 0
	v_addc_co_u32_e32 v81, vcc, 0, v93, vcc
	v_add_co_u32_e32 v84, vcc, s52, v92
	s_nop 0
	v_addc_co_u32_e32 v85, vcc, 0, v93, vcc
	v_add_co_u32_e32 v88, vcc, s33, v92
	s_nop 0
	v_addc_co_u32_e32 v89, vcc, 0, v93, vcc
	s_mov_b32 s2, 0x1c000
	v_add_co_u32_e32 v92, vcc, s2, v92
	s_nop 0
	v_addc_co_u32_e32 v93, vcc, 0, v93, vcc
	s_movk_i32 s2, 0x2000
	s_mov_b32 s42, 0x8000
	s_waitcnt vmcnt(0)
	ds_write_b128 v140, v[206:209]
	ds_write_b128 v140, v[210:213] offset:1024
	ds_write_b128 v140, v[214:217] offset:2048
	ds_write_b128 v140, v[218:221] offset:3072
	ds_write_b128 v140, v[222:225] offset:4096
	ds_write_b128 v140, v[226:229] offset:5120
	ds_write_b128 v140, v[230:233] offset:6144
	ds_write_b128 v140, v[234:237] offset:7168
	v_mul_f32_e32 v64, v16, v16
	v_mul_f32_e32 v65, v32, v32
	v_fmac_f32_e32 v64, v0, v0
	v_fmac_f32_e32 v65, v48, v48
	v_add_f32_e32 v64, v64, v65
	ds_read_u16 v144, v138
	ds_read_u16 v145, v138 offset:64
	ds_read_u16 v146, v138 offset:128
	ds_read_u16 v147, v138 offset:192
	s_nop 1
	v_add_f32_dpp v64, v64, v64 quad_perm:[1,0,3,2] row_mask:0xf bank_mask:0xf
	s_nop 1
	v_add_f32_dpp v64, v64, v64 quad_perm:[2,3,0,1] row_mask:0xf bank_mask:0xf
	s_nop 1
	v_add_f32_dpp v64, v64, v64 row_half_mirror row_mask:0xf bank_mask:0xf
	s_nop 1
	v_add_f32_dpp v64, v64, v64 row_mirror row_mask:0xf bank_mask:0xf
	s_waitcnt lgkmcnt(0)
	ds_bpermute_b32 v65, v137, v64
	s_waitcnt lgkmcnt(0)
	v_add_f32_e32 v64, v64, v65
	v_fmamk_f32 v64, v64, 0x3c000000, v199
	v_rsq_f32_e32 v64, v64
	v_lshlrev_b32_e32 v65, 16, v144
	v_mul_f32_e32 v66, 0xbfb8aa3b, v65
	v_exp_f32_e32 v66, v66
	v_mul_f32_e32 v0, v0, v64
	v_mul_f32_e32 v0, v113, v0
	v_mul_f32_e32 v16, v16, v64
	v_add_f32_e32 v66, 1.0, v66
	v_rcp_f32_e32 v66, v66
	v_mul_f32_e32 v16, v130, v16
	v_mul_f32_e32 v65, v66, v65
	v_mul_f32_e32 v0, v0, v65
	v_cvt_pk_bf16_f32 v0, v0, s0
	ds_write_b16 v138, v0 offset:8192
	v_lshlrev_b32_e32 v0, 16, v145
	v_mul_f32_e32 v65, 0xbfb8aa3b, v0
	v_exp_f32_e32 v65, v65
	s_nop 0
	v_add_f32_e32 v65, 1.0, v65
	v_rcp_f32_e32 v65, v65
	s_nop 0
	v_mul_f32_e32 v0, v65, v0
	v_mul_f32_e32 v0, v16, v0
	v_cvt_pk_bf16_f32 v0, v0, s0
	ds_write_b16 v138, v0 offset:8256
	v_mul_f32_e32 v16, v48, v64
	v_mul_f32_e32 v16, v131, v16
	v_lshlrev_b32_e32 v0, 16, v146
	v_mul_f32_e32 v48, 0xbfb8aa3b, v0
	v_exp_f32_e32 v48, v48
	s_nop 0
	v_add_f32_e32 v48, 1.0, v48
	v_rcp_f32_e32 v48, v48
	s_nop 0
	v_mul_f32_e32 v0, v48, v0
	v_mul_f32_e32 v0, v16, v0
	v_cvt_pk_bf16_f32 v0, v0, s0
	ds_write_b16 v138, v0 offset:8320
	v_mul_f32_e32 v16, v32, v64
	v_mul_f32_e32 v16, v132, v16
	v_lshlrev_b32_e32 v0, 16, v147
	v_mul_f32_e32 v32, 0xbfb8aa3b, v0
	v_exp_f32_e32 v32, v32
	s_nop 0
	v_add_f32_e32 v32, 1.0, v32
	v_rcp_f32_e32 v32, v32
	s_nop 0
	v_mul_f32_e32 v0, v32, v0
	v_mul_f32_e32 v0, v16, v0
	v_cvt_pk_bf16_f32 v0, v0, s0
	ds_write_b16 v138, v0 offset:8384
	v_mul_f32_e32 v0, v17, v17
	v_mul_f32_e32 v16, v33, v33
	v_fmac_f32_e32 v0, v1, v1
	v_fmac_f32_e32 v16, v49, v49
	v_add_f32_e32 v0, v0, v16
	ds_read_u16 v144, v138 offset:256
	ds_read_u16 v145, v138 offset:320
	ds_read_u16 v146, v138 offset:384
	ds_read_u16 v147, v138 offset:448
	s_nop 1
	v_add_f32_dpp v0, v0, v0 quad_perm:[1,0,3,2] row_mask:0xf bank_mask:0xf
	s_nop 1
	v_add_f32_dpp v0, v0, v0 quad_perm:[2,3,0,1] row_mask:0xf bank_mask:0xf
	s_nop 1
	v_add_f32_dpp v0, v0, v0 row_half_mirror row_mask:0xf bank_mask:0xf
	s_nop 1
	v_add_f32_dpp v0, v0, v0 row_mirror row_mask:0xf bank_mask:0xf
	s_waitcnt lgkmcnt(0)
	ds_bpermute_b32 v16, v137, v0
	s_waitcnt lgkmcnt(0)
	v_add_f32_e32 v0, v0, v16
	v_fmamk_f32 v0, v0, 0x3c000000, v199
	v_rsq_f32_e32 v0, v0
	v_lshlrev_b32_e32 v16, 16, v144
	v_mul_f32_e32 v32, 0xbfb8aa3b, v16
	v_exp_f32_e32 v32, v32
	v_mul_f32_e32 v1, v1, v0
	v_mul_f32_e32 v1, v113, v1
	v_add_f32_e32 v32, 1.0, v32
	v_rcp_f32_e32 v32, v32
	s_nop 0
	v_mul_f32_e32 v16, v32, v16
	v_mul_f32_e32 v1, v1, v16
	v_cvt_pk_bf16_f32 v1, v1, s0
	ds_write_b16 v138, v1 offset:8448
	v_mul_f32_e32 v16, v17, v0
	v_mul_f32_e32 v16, v130, v16
	v_lshlrev_b32_e32 v1, 16, v145
	v_mul_f32_e32 v17, 0xbfb8aa3b, v1
	v_exp_f32_e32 v17, v17
	s_nop 0
	v_add_f32_e32 v17, 1.0, v17
	v_rcp_f32_e32 v17, v17
	s_nop 0
	v_mul_f32_e32 v1, v17, v1
	v_mul_f32_e32 v1, v16, v1
	v_cvt_pk_bf16_f32 v1, v1, s0
	ds_write_b16 v138, v1 offset:8512
	v_mul_f32_e32 v16, v49, v0
	v_mul_f32_e32 v16, v131, v16
	v_mul_f32_e32 v0, v33, v0
	v_mul_f32_e32 v0, v132, v0
	v_lshlrev_b32_e32 v1, 16, v146
	v_mul_f32_e32 v17, 0xbfb8aa3b, v1
	v_exp_f32_e32 v17, v17
	s_nop 0
	v_add_f32_e32 v17, 1.0, v17
	v_rcp_f32_e32 v17, v17
	s_nop 0
	v_mul_f32_e32 v1, v17, v1
	v_mul_f32_e32 v1, v16, v1
	v_cvt_pk_bf16_f32 v1, v1, s0
	ds_write_b16 v138, v1 offset:8576
	v_lshlrev_b32_e32 v1, 16, v147
	v_mul_f32_e32 v16, 0xbfb8aa3b, v1
	v_exp_f32_e32 v16, v16
	s_nop 0
	v_add_f32_e32 v16, 1.0, v16
	v_rcp_f32_e32 v16, v16
	s_nop 0
	v_mul_f32_e32 v1, v16, v1
	v_mul_f32_e32 v0, v0, v1
	v_cvt_pk_bf16_f32 v0, v0, s0
	ds_write_b16 v138, v0 offset:8640
	v_mul_f32_e32 v0, v18, v18
	v_mul_f32_e32 v1, v34, v34
	v_fmac_f32_e32 v0, v2, v2
	v_fmac_f32_e32 v1, v50, v50
	v_add_f32_e32 v0, v0, v1
	ds_read_u16 v144, v138 offset:512
	ds_read_u16 v145, v138 offset:576
	ds_read_u16 v146, v138 offset:640
	ds_read_u16 v147, v138 offset:704
	s_nop 1
	v_add_f32_dpp v0, v0, v0 quad_perm:[1,0,3,2] row_mask:0xf bank_mask:0xf
	s_nop 1
	v_add_f32_dpp v0, v0, v0 quad_perm:[2,3,0,1] row_mask:0xf bank_mask:0xf
	s_nop 1
	v_add_f32_dpp v0, v0, v0 row_half_mirror row_mask:0xf bank_mask:0xf
	s_nop 1
	v_add_f32_dpp v0, v0, v0 row_mirror row_mask:0xf bank_mask:0xf
	s_waitcnt lgkmcnt(0)
; __device__ __forceinline__ int crow(int r, int hi) { return (r & 3) + 8 * (r >> 2) + 4 * hi; }
; __device__ __forceinline__ float bf2f(unsigned short v) { return __uint_as_float((unsigned)v << 16); }
; __device__ __forceinline__ unsigned f2bf(float f) { return pk2(f, 0.f) & 0xffffu; }
; __device__ __forceinline__ int crow(int r, int hi) { return (r & 3) + 8 * (r >> 2) + 4 * hi; }
; __device__ __forceinline__ void gla_pass_c(LAS unsigned char* ldsl, const bf16_t* __restrict__ proj, const float* __restrict__ Btab, const float* __restrict__ Gst, const float* __restrict__ gout, bf16_t* __restrict__ mixed) {
;     ...
;         for (int i = 0; i < 16; ++i) { const int tr = crow(i, hh);
;             const float tot = half_sum32((o[0][i] * o[0][i] + o[1][i] * o[1][i]) + (o[2][i] * o[2][i] + o[3][i] * o[3][i]));
;             const float rr = __builtin_amdgcn_rsqf(tot * (1.0f / 128.0f) + EPS);
; #pragma unroll
;             for (int dvb = 0; dvb < 4; ++dvb) { const float g = bf2f(Lh[tr * 128 + 32 * dvb + r]);
;                 const float val = o[dvb][i] * rr * gn[dvb] * (g * __builtin_amdgcn_rcpf(1.0f + __expf(-g)));
;                 Lh[(32 + tr) * 128 + 32 * dvb + r] = (bf16_t)f2bf(val); } }
	ds_bpermute_b32 v1, v137, v0
	s_waitcnt lgkmcnt(0)
	v_add_f32_e32 v0, v0, v1
	v_fmamk_f32 v0, v0, 0x3c000000, v199
	v_rsq_f32_e32 v0, v0
	v_lshlrev_b32_e32 v1, 16, v144
	v_mul_f32_e32 v16, 0xbfb8aa3b, v1
	v_exp_f32_e32 v16, v16
	v_mul_f32_e32 v2, v2, v0
	v_mul_f32_e32 v2, v113, v2
	v_add_f32_e32 v16, 1.0, v16
	v_rcp_f32_e32 v16, v16
	s_nop 0
	v_mul_f32_e32 v1, v16, v1
	v_mul_f32_e32 v1, v2, v1
	v_cvt_pk_bf16_f32 v1, v1, s0
	ds_write_b16 v138, v1 offset:8704
	v_mul_f32_e32 v2, v18, v0
	v_mul_f32_e32 v2, v130, v2
	v_lshlrev_b32_e32 v1, 16, v145
	v_mul_f32_e32 v16, 0xbfb8aa3b, v1
	v_exp_f32_e32 v16, v16
	s_nop 0
	v_add_f32_e32 v16, 1.0, v16
	v_rcp_f32_e32 v16, v16
	s_nop 0
	v_mul_f32_e32 v1, v16, v1
	v_mul_f32_e32 v1, v2, v1
	v_cvt_pk_bf16_f32 v1, v1, s0
	ds_write_b16 v138, v1 offset:8768
	v_mul_f32_e32 v2, v50, v0
	v_mul_f32_e32 v2, v131, v2
	v_mul_f32_e32 v0, v34, v0
	v_mul_f32_e32 v0, v132, v0
	v_lshlrev_b32_e32 v1, 16, v146
	v_mul_f32_e32 v16, 0xbfb8aa3b, v1
	v_exp_f32_e32 v16, v16
	s_nop 0
	v_add_f32_e32 v16, 1.0, v16
	v_rcp_f32_e32 v16, v16
	s_nop 0
	v_mul_f32_e32 v1, v16, v1
	v_mul_f32_e32 v1, v2, v1
	v_cvt_pk_bf16_f32 v1, v1, s0
	ds_write_b16 v138, v1 offset:8832
	v_lshlrev_b32_e32 v1, 16, v147
	v_mul_f32_e32 v2, 0xbfb8aa3b, v1
	v_exp_f32_e32 v2, v2
	s_nop 0
	v_add_f32_e32 v2, 1.0, v2
	v_rcp_f32_e32 v2, v2
	s_nop 0
	v_mul_f32_e32 v1, v2, v1
	v_mul_f32_e32 v0, v0, v1
	v_cvt_pk_bf16_f32 v0, v0, s0
	ds_write_b16 v138, v0 offset:8896
	v_mul_f32_e32 v0, v19, v19
	v_mul_f32_e32 v1, v35, v35
	v_fmac_f32_e32 v0, v3, v3
	v_fmac_f32_e32 v1, v51, v51
	v_add_f32_e32 v0, v0, v1
	ds_read_u16 v144, v138 offset:768
	ds_read_u16 v145, v138 offset:832
	ds_read_u16 v146, v138 offset:896
	ds_read_u16 v147, v138 offset:960
	s_nop 1
	v_add_f32_dpp v0, v0, v0 quad_perm:[1,0,3,2] row_mask:0xf bank_mask:0xf
	s_nop 1
	v_add_f32_dpp v0, v0, v0 quad_perm:[2,3,0,1] row_mask:0xf bank_mask:0xf
	s_nop 1
	v_add_f32_dpp v0, v0, v0 row_half_mirror row_mask:0xf bank_mask:0xf
	s_nop 1
	v_add_f32_dpp v0, v0, v0 row_mirror row_mask:0xf bank_mask:0xf
	s_waitcnt lgkmcnt(0)
	ds_bpermute_b32 v1, v137, v0
	s_waitcnt lgkmcnt(0)
	v_add_f32_e32 v0, v0, v1
	v_fmamk_f32 v0, v0, 0x3c000000, v199
	v_rsq_f32_e32 v0, v0
	v_lshlrev_b32_e32 v1, 16, v144
	v_mul_f32_e32 v2, v3, v0
	v_mul_f32_e32 v3, 0xbfb8aa3b, v1
	v_exp_f32_e32 v3, v3
	v_mul_f32_e32 v2, v113, v2
	v_add_f32_e32 v3, 1.0, v3
	v_rcp_f32_e32 v3, v3
	s_nop 0
	v_mul_f32_e32 v1, v3, v1
	v_mul_f32_e32 v1, v2, v1
	v_cvt_pk_bf16_f32 v1, v1, s0
	ds_write_b16 v138, v1 offset:8960
	v_mul_f32_e32 v2, v19, v0
	v_mul_f32_e32 v2, v130, v2
	v_lshlrev_b32_e32 v1, 16, v145
	v_mul_f32_e32 v3, 0xbfb8aa3b, v1
	v_exp_f32_e32 v3, v3
	s_nop 0
	v_add_f32_e32 v3, 1.0, v3
	v_rcp_f32_e32 v3, v3
	s_nop 0
	v_mul_f32_e32 v1, v3, v1
	v_mul_f32_e32 v1, v2, v1
	v_cvt_pk_bf16_f32 v1, v1, s0
	ds_write_b16 v138, v1 offset:9024
	v_mul_f32_e32 v2, v51, v0
	v_mul_f32_e32 v2, v131, v2
	v_mul_f32_e32 v0, v35, v0
	v_mul_f32_e32 v0, v132, v0
	v_lshlrev_b32_e32 v1, 16, v146
	v_mul_f32_e32 v3, 0xbfb8aa3b, v1
	v_exp_f32_e32 v3, v3
	s_nop 0
	v_add_f32_e32 v3, 1.0, v3
	v_rcp_f32_e32 v3, v3
	s_nop 0
	v_mul_f32_e32 v1, v3, v1
	v_mul_f32_e32 v1, v2, v1
	v_cvt_pk_bf16_f32 v1, v1, s0
	ds_write_b16 v138, v1 offset:9088
	v_lshlrev_b32_e32 v1, 16, v147
	v_mul_f32_e32 v2, 0xbfb8aa3b, v1
	v_exp_f32_e32 v2, v2
	s_nop 0
	v_add_f32_e32 v2, 1.0, v2
	v_rcp_f32_e32 v2, v2
	s_nop 0
	v_mul_f32_e32 v1, v2, v1
	v_mul_f32_e32 v0, v0, v1
	v_cvt_pk_bf16_f32 v0, v0, s0
	ds_write_b16 v138, v0 offset:9152
	v_mul_f32_e32 v0, v20, v20
	v_mul_f32_e32 v1, v36, v36
	v_fmac_f32_e32 v0, v4, v4
	v_fmac_f32_e32 v1, v52, v52
	v_add_f32_e32 v0, v0, v1
	ds_read_u16 v144, v138 offset:2048
	ds_read_u16 v145, v138 offset:2112
	ds_read_u16 v146, v138 offset:2176
	ds_read_u16 v147, v138 offset:2240
	s_nop 1
	v_add_f32_dpp v0, v0, v0 quad_perm:[1,0,3,2] row_mask:0xf bank_mask:0xf
	s_nop 1
	v_add_f32_dpp v0, v0, v0 quad_perm:[2,3,0,1] row_mask:0xf bank_mask:0xf
	s_nop 1
	v_add_f32_dpp v0, v0, v0 row_half_mirror row_mask:0xf bank_mask:0xf
	s_nop 1
	v_add_f32_dpp v0, v0, v0 row_mirror row_mask:0xf bank_mask:0xf
	s_waitcnt lgkmcnt(0)
	ds_bpermute_b32 v1, v137, v0
	s_waitcnt lgkmcnt(0)
	v_add_f32_e32 v0, v0, v1
	v_fmamk_f32 v0, v0, 0x3c000000, v199
	v_rsq_f32_e32 v0, v0
	v_lshlrev_b32_e32 v1, 16, v144
	v_mul_f32_e32 v3, 0xbfb8aa3b, v1
	v_exp_f32_e32 v3, v3
	v_mul_f32_e32 v2, v4, v0
	v_mul_f32_e32 v2, v113, v2
	v_add_f32_e32 v3, 1.0, v3
	v_rcp_f32_e32 v3, v3
	s_nop 0
	v_mul_f32_e32 v1, v3, v1
	v_mul_f32_e32 v1, v2, v1
	v_cvt_pk_bf16_f32 v1, v1, s0
	ds_write_b16 v138, v1 offset:10240
	v_mul_f32_e32 v2, v20, v0
	v_mul_f32_e32 v2, v130, v2
	v_lshlrev_b32_e32 v1, 16, v145
	v_mul_f32_e32 v3, 0xbfb8aa3b, v1
	v_exp_f32_e32 v3, v3
	s_nop 0
	v_add_f32_e32 v3, 1.0, v3
	v_rcp_f32_e32 v3, v3
	s_nop 0
	v_mul_f32_e32 v1, v3, v1
	v_mul_f32_e32 v1, v2, v1
	v_cvt_pk_bf16_f32 v1, v1, s0
	ds_write_b16 v138, v1 offset:10304
	v_mul_f32_e32 v2, v52, v0
	v_mul_f32_e32 v2, v131, v2
	v_mul_f32_e32 v0, v36, v0
	v_mul_f32_e32 v0, v132, v0
	v_lshlrev_b32_e32 v1, 16, v146
	v_mul_f32_e32 v3, 0xbfb8aa3b, v1
	v_exp_f32_e32 v3, v3
	s_nop 0
	v_add_f32_e32 v3, 1.0, v3
	v_rcp_f32_e32 v3, v3
	s_nop 0
	v_mul_f32_e32 v1, v3, v1
	v_mul_f32_e32 v1, v2, v1
	v_cvt_pk_bf16_f32 v1, v1, s0
	ds_write_b16 v138, v1 offset:10368
	v_lshlrev_b32_e32 v1, 16, v147
	v_mul_f32_e32 v2, 0xbfb8aa3b, v1
	v_exp_f32_e32 v2, v2
	s_nop 0
	v_add_f32_e32 v2, 1.0, v2
	v_rcp_f32_e32 v2, v2
	s_nop 0
	v_mul_f32_e32 v1, v2, v1
	v_mul_f32_e32 v0, v0, v1
	v_cvt_pk_bf16_f32 v0, v0, s0
	ds_write_b16 v138, v0 offset:10432
	v_mul_f32_e32 v0, v21, v21
	v_mul_f32_e32 v1, v37, v37
	v_fmac_f32_e32 v0, v5, v5
	v_fmac_f32_e32 v1, v53, v53
	v_add_f32_e32 v0, v0, v1
	ds_read_u16 v144, v138 offset:2304
	ds_read_u16 v145, v138 offset:2368
	ds_read_u16 v146, v138 offset:2432
	ds_read_u16 v147, v138 offset:2496
	s_nop 1
	v_add_f32_dpp v0, v0, v0 quad_perm:[1,0,3,2] row_mask:0xf bank_mask:0xf
	s_nop 1
	v_add_f32_dpp v0, v0, v0 quad_perm:[2,3,0,1] row_mask:0xf bank_mask:0xf
	s_nop 1
	v_add_f32_dpp v0, v0, v0 row_half_mirror row_mask:0xf bank_mask:0xf
	s_nop 1
	v_add_f32_dpp v0, v0, v0 row_mirror row_mask:0xf bank_mask:0xf
	s_waitcnt lgkmcnt(0)
; __device__ __forceinline__ int crow(int r, int hi) { return (r & 3) + 8 * (r >> 2) + 4 * hi; }
; __device__ __forceinline__ float bf2f(unsigned short v) { return __uint_as_float((unsigned)v << 16); }
; __device__ __forceinline__ unsigned f2bf(float f) { return pk2(f, 0.f) & 0xffffu; }
; __device__ __forceinline__ int crow(int r, int hi) { return (r & 3) + 8 * (r >> 2) + 4 * hi; }
; __device__ __forceinline__ void gla_pass_c(LAS unsigned char* ldsl, const bf16_t* __restrict__ proj, const float* __restrict__ Btab, const float* __restrict__ Gst, const float* __restrict__ gout, bf16_t* __restrict__ mixed) {
;     ...
;         for (int i = 0; i < 16; ++i) { const int tr = crow(i, hh);
;             const float tot = half_sum32((o[0][i] * o[0][i] + o[1][i] * o[1][i]) + (o[2][i] * o[2][i] + o[3][i] * o[3][i]));
;             const float rr = __builtin_amdgcn_rsqf(tot * (1.0f / 128.0f) + EPS);
; #pragma unroll
;             for (int dvb = 0; dvb < 4; ++dvb) { const float g = bf2f(Lh[tr * 128 + 32 * dvb + r]);
;                 const float val = o[dvb][i] * rr * gn[dvb] * (g * __builtin_amdgcn_rcpf(1.0f + __expf(-g)));
;                 Lh[(32 + tr) * 128 + 32 * dvb + r] = (bf16_t)f2bf(val); } }
	ds_bpermute_b32 v1, v137, v0
	s_waitcnt lgkmcnt(0)
	v_add_f32_e32 v0, v0, v1
	v_fmamk_f32 v0, v0, 0x3c000000, v199
	v_rsq_f32_e32 v0, v0
	v_lshlrev_b32_e32 v1, 16, v144
	v_mul_f32_e32 v3, 0xbfb8aa3b, v1
	v_exp_f32_e32 v3, v3
	v_mul_f32_e32 v2, v5, v0
	v_mul_f32_e32 v2, v113, v2
	v_add_f32_e32 v3, 1.0, v3
	v_rcp_f32_e32 v3, v3
	s_nop 0
	v_mul_f32_e32 v1, v3, v1
	v_mul_f32_e32 v1, v2, v1
	v_cvt_pk_bf16_f32 v1, v1, s0
	ds_write_b16 v138, v1 offset:10496
	v_mul_f32_e32 v2, v21, v0
	v_mul_f32_e32 v2, v130, v2
	v_lshlrev_b32_e32 v1, 16, v145
	v_mul_f32_e32 v3, 0xbfb8aa3b, v1
	v_exp_f32_e32 v3, v3
	s_nop 0
	v_add_f32_e32 v3, 1.0, v3
	v_rcp_f32_e32 v3, v3
	s_nop 0
	v_mul_f32_e32 v1, v3, v1
	v_mul_f32_e32 v1, v2, v1
	v_cvt_pk_bf16_f32 v1, v1, s0
	ds_write_b16 v138, v1 offset:10560
	v_mul_f32_e32 v2, v53, v0
	v_mul_f32_e32 v2, v131, v2
	v_mul_f32_e32 v0, v37, v0
	v_mul_f32_e32 v0, v132, v0
	v_lshlrev_b32_e32 v1, 16, v146
	v_mul_f32_e32 v3, 0xbfb8aa3b, v1
	v_exp_f32_e32 v3, v3
	s_nop 0
	v_add_f32_e32 v3, 1.0, v3
	v_rcp_f32_e32 v3, v3
	s_nop 0
	v_mul_f32_e32 v1, v3, v1
	v_mul_f32_e32 v1, v2, v1
	v_cvt_pk_bf16_f32 v1, v1, s0
	ds_write_b16 v138, v1 offset:10624
	v_lshlrev_b32_e32 v1, 16, v147
	v_mul_f32_e32 v2, 0xbfb8aa3b, v1
	v_exp_f32_e32 v2, v2
	s_nop 0
	v_add_f32_e32 v2, 1.0, v2
	v_rcp_f32_e32 v2, v2
	s_nop 0
	v_mul_f32_e32 v1, v2, v1
	v_mul_f32_e32 v0, v0, v1
	v_cvt_pk_bf16_f32 v0, v0, s0
	ds_write_b16 v138, v0 offset:10688
	v_mul_f32_e32 v0, v22, v22
	v_mul_f32_e32 v1, v38, v38
	v_fmac_f32_e32 v0, v6, v6
	v_fmac_f32_e32 v1, v54, v54
	v_add_f32_e32 v0, v0, v1
	ds_read_u16 v144, v138 offset:2560
	ds_read_u16 v145, v138 offset:2624
	ds_read_u16 v146, v138 offset:2688
	ds_read_u16 v147, v138 offset:2752
	s_nop 1
	v_add_f32_dpp v0, v0, v0 quad_perm:[1,0,3,2] row_mask:0xf bank_mask:0xf
	s_nop 1
	v_add_f32_dpp v0, v0, v0 quad_perm:[2,3,0,1] row_mask:0xf bank_mask:0xf
	s_nop 1
	v_add_f32_dpp v0, v0, v0 row_half_mirror row_mask:0xf bank_mask:0xf
	s_nop 1
	v_add_f32_dpp v0, v0, v0 row_mirror row_mask:0xf bank_mask:0xf
	s_waitcnt lgkmcnt(0)
	ds_bpermute_b32 v1, v137, v0
	s_waitcnt lgkmcnt(0)
	v_add_f32_e32 v0, v0, v1
	v_fmamk_f32 v0, v0, 0x3c000000, v199
	v_rsq_f32_e32 v0, v0
	v_lshlrev_b32_e32 v1, 16, v144
	v_mul_f32_e32 v3, 0xbfb8aa3b, v1
	v_exp_f32_e32 v3, v3
	v_mul_f32_e32 v2, v6, v0
	v_mul_f32_e32 v2, v113, v2
	v_add_f32_e32 v3, 1.0, v3
	v_rcp_f32_e32 v3, v3
	s_nop 0
	v_mul_f32_e32 v1, v3, v1
	v_mul_f32_e32 v1, v2, v1
	v_cvt_pk_bf16_f32 v1, v1, s0
	ds_write_b16 v138, v1 offset:10752
	v_mul_f32_e32 v2, v22, v0
	v_mul_f32_e32 v2, v130, v2
	v_lshlrev_b32_e32 v1, 16, v145
	v_mul_f32_e32 v3, 0xbfb8aa3b, v1
	v_exp_f32_e32 v3, v3
	s_nop 0
	v_add_f32_e32 v3, 1.0, v3
	v_rcp_f32_e32 v3, v3
	s_nop 0
	v_mul_f32_e32 v1, v3, v1
	v_mul_f32_e32 v1, v2, v1
	v_cvt_pk_bf16_f32 v1, v1, s0
	ds_write_b16 v138, v1 offset:10816
	v_mul_f32_e32 v2, v54, v0
	v_mul_f32_e32 v2, v131, v2
	v_mul_f32_e32 v0, v38, v0
	v_mul_f32_e32 v0, v132, v0
	v_lshlrev_b32_e32 v1, 16, v146
	v_mul_f32_e32 v3, 0xbfb8aa3b, v1
	v_exp_f32_e32 v3, v3
	s_nop 0
	v_add_f32_e32 v3, 1.0, v3
	v_rcp_f32_e32 v3, v3
	s_nop 0
	v_mul_f32_e32 v1, v3, v1
	v_mul_f32_e32 v1, v2, v1
	v_cvt_pk_bf16_f32 v1, v1, s0
	ds_write_b16 v138, v1 offset:10880
	v_lshlrev_b32_e32 v1, 16, v147
	v_mul_f32_e32 v2, 0xbfb8aa3b, v1
	v_exp_f32_e32 v2, v2
	s_nop 0
	v_add_f32_e32 v2, 1.0, v2
	v_rcp_f32_e32 v2, v2
	s_nop 0
	v_mul_f32_e32 v1, v2, v1
	v_mul_f32_e32 v0, v0, v1
	v_cvt_pk_bf16_f32 v0, v0, s0
	ds_write_b16 v138, v0 offset:10944
	v_mul_f32_e32 v0, v23, v23
	v_mul_f32_e32 v1, v39, v39
	v_fmac_f32_e32 v0, v7, v7
	v_fmac_f32_e32 v1, v55, v55
	v_add_f32_e32 v0, v0, v1
	ds_read_u16 v144, v138 offset:2816
	ds_read_u16 v145, v138 offset:2880
	ds_read_u16 v146, v138 offset:2944
	ds_read_u16 v147, v138 offset:3008
	s_nop 1
	v_add_f32_dpp v0, v0, v0 quad_perm:[1,0,3,2] row_mask:0xf bank_mask:0xf
	s_nop 1
	v_add_f32_dpp v0, v0, v0 quad_perm:[2,3,0,1] row_mask:0xf bank_mask:0xf
	s_nop 1
	v_add_f32_dpp v0, v0, v0 row_half_mirror row_mask:0xf bank_mask:0xf
	s_nop 1
	v_add_f32_dpp v0, v0, v0 row_mirror row_mask:0xf bank_mask:0xf
	s_waitcnt lgkmcnt(0)
	ds_bpermute_b32 v1, v137, v0
	s_waitcnt lgkmcnt(0)
	v_add_f32_e32 v0, v0, v1
	v_fmamk_f32 v0, v0, 0x3c000000, v199
	v_rsq_f32_e32 v0, v0
	v_lshlrev_b32_e32 v1, 16, v144
	v_mul_f32_e32 v3, 0xbfb8aa3b, v1
	v_exp_f32_e32 v3, v3
	v_mul_f32_e32 v2, v7, v0
	v_mul_f32_e32 v2, v113, v2
	v_add_f32_e32 v3, 1.0, v3
	v_rcp_f32_e32 v3, v3
	s_nop 0
	v_mul_f32_e32 v1, v3, v1
	v_mul_f32_e32 v1, v2, v1
	v_cvt_pk_bf16_f32 v1, v1, s0
	ds_write_b16 v138, v1 offset:11008
	v_mul_f32_e32 v2, v23, v0
	v_mul_f32_e32 v2, v130, v2
	v_lshlrev_b32_e32 v1, 16, v145
	v_mul_f32_e32 v3, 0xbfb8aa3b, v1
	v_exp_f32_e32 v3, v3
	s_nop 0
	v_add_f32_e32 v3, 1.0, v3
	v_rcp_f32_e32 v3, v3
	s_nop 0
	v_mul_f32_e32 v1, v3, v1
	v_mul_f32_e32 v1, v2, v1
	v_cvt_pk_bf16_f32 v1, v1, s0
	ds_write_b16 v138, v1 offset:11072
	v_mul_f32_e32 v2, v55, v0
	v_mul_f32_e32 v2, v131, v2
	v_mul_f32_e32 v0, v39, v0
	v_mul_f32_e32 v0, v132, v0
	v_lshlrev_b32_e32 v1, 16, v146
	v_mul_f32_e32 v3, 0xbfb8aa3b, v1
	v_exp_f32_e32 v3, v3
	s_nop 0
	v_add_f32_e32 v3, 1.0, v3
	v_rcp_f32_e32 v3, v3
	s_nop 0
	v_mul_f32_e32 v1, v3, v1
	v_mul_f32_e32 v1, v2, v1
	v_cvt_pk_bf16_f32 v1, v1, s0
	ds_write_b16 v138, v1 offset:11136
	v_lshlrev_b32_e32 v1, 16, v147
	v_mul_f32_e32 v2, 0xbfb8aa3b, v1
	v_exp_f32_e32 v2, v2
	s_nop 0
	v_add_f32_e32 v2, 1.0, v2
	v_rcp_f32_e32 v2, v2
	s_nop 0
	v_mul_f32_e32 v1, v2, v1
	v_mul_f32_e32 v0, v0, v1
	v_cvt_pk_bf16_f32 v0, v0, s0
	ds_write_b16 v138, v0 offset:11200
	v_mul_f32_e32 v0, v24, v24
	v_mul_f32_e32 v1, v40, v40
	v_fmac_f32_e32 v0, v8, v8
	v_fmac_f32_e32 v1, v56, v56
	v_add_f32_e32 v0, v0, v1
	ds_read_u16 v144, v138 offset:4096
	ds_read_u16 v145, v138 offset:4160
	ds_read_u16 v146, v138 offset:4224
	ds_read_u16 v147, v138 offset:4288
	s_nop 1
	v_add_f32_dpp v0, v0, v0 quad_perm:[1,0,3,2] row_mask:0xf bank_mask:0xf
	s_nop 1
	v_add_f32_dpp v0, v0, v0 quad_perm:[2,3,0,1] row_mask:0xf bank_mask:0xf
	s_nop 1
	v_add_f32_dpp v0, v0, v0 row_half_mirror row_mask:0xf bank_mask:0xf
	s_nop 1
	v_add_f32_dpp v0, v0, v0 row_mirror row_mask:0xf bank_mask:0xf
	s_waitcnt lgkmcnt(0)
; __device__ __forceinline__ int crow(int r, int hi) { return (r & 3) + 8 * (r >> 2) + 4 * hi; }
; __device__ __forceinline__ float bf2f(unsigned short v) { return __uint_as_float((unsigned)v << 16); }
; __device__ __forceinline__ unsigned f2bf(float f) { return pk2(f, 0.f) & 0xffffu; }
; __device__ __forceinline__ int crow(int r, int hi) { return (r & 3) + 8 * (r >> 2) + 4 * hi; }
; __device__ __forceinline__ void gla_pass_c(LAS unsigned char* ldsl, const bf16_t* __restrict__ proj, const float* __restrict__ Btab, const float* __restrict__ Gst, const float* __restrict__ gout, bf16_t* __restrict__ mixed) {
;     ...
;         for (int i = 0; i < 16; ++i) { const int tr = crow(i, hh);
;             const float tot = half_sum32((o[0][i] * o[0][i] + o[1][i] * o[1][i]) + (o[2][i] * o[2][i] + o[3][i] * o[3][i]));
;             const float rr = __builtin_amdgcn_rsqf(tot * (1.0f / 128.0f) + EPS);
; #pragma unroll
;             for (int dvb = 0; dvb < 4; ++dvb) { const float g = bf2f(Lh[tr * 128 + 32 * dvb + r]);
;                 const float val = o[dvb][i] * rr * gn[dvb] * (g * __builtin_amdgcn_rcpf(1.0f + __expf(-g)));
;                 Lh[(32 + tr) * 128 + 32 * dvb + r] = (bf16_t)f2bf(val); } }
	ds_bpermute_b32 v1, v137, v0
	s_waitcnt lgkmcnt(0)
	v_add_f32_e32 v0, v0, v1
	v_fmamk_f32 v0, v0, 0x3c000000, v199
	v_rsq_f32_e32 v0, v0
	v_lshlrev_b32_e32 v1, 16, v144
	v_mul_f32_e32 v3, 0xbfb8aa3b, v1
	v_exp_f32_e32 v3, v3
	v_mul_f32_e32 v2, v8, v0
	v_mul_f32_e32 v2, v113, v2
	v_add_f32_e32 v3, 1.0, v3
	v_rcp_f32_e32 v3, v3
	s_nop 0
	v_mul_f32_e32 v1, v3, v1
	v_mul_f32_e32 v1, v2, v1
	v_cvt_pk_bf16_f32 v1, v1, s0
	ds_write_b16 v138, v1 offset:12288
	v_mul_f32_e32 v2, v24, v0
	v_mul_f32_e32 v2, v130, v2
	v_lshlrev_b32_e32 v1, 16, v145
	v_mul_f32_e32 v3, 0xbfb8aa3b, v1
	v_exp_f32_e32 v3, v3
	s_nop 0
	v_add_f32_e32 v3, 1.0, v3
	v_rcp_f32_e32 v3, v3
	s_nop 0
	v_mul_f32_e32 v1, v3, v1
	v_mul_f32_e32 v1, v2, v1
	v_cvt_pk_bf16_f32 v1, v1, s0
	ds_write_b16 v138, v1 offset:12352
	v_mul_f32_e32 v2, v56, v0
	v_mul_f32_e32 v2, v131, v2
	v_mul_f32_e32 v0, v40, v0
	v_mul_f32_e32 v0, v132, v0
	v_lshlrev_b32_e32 v1, 16, v146
	v_mul_f32_e32 v3, 0xbfb8aa3b, v1
	v_exp_f32_e32 v3, v3
	s_nop 0
	v_add_f32_e32 v3, 1.0, v3
	v_rcp_f32_e32 v3, v3
	s_nop 0
	v_mul_f32_e32 v1, v3, v1
	v_mul_f32_e32 v1, v2, v1
	v_cvt_pk_bf16_f32 v1, v1, s0
	ds_write_b16 v138, v1 offset:12416
	v_lshlrev_b32_e32 v1, 16, v147
	v_mul_f32_e32 v2, 0xbfb8aa3b, v1
	v_exp_f32_e32 v2, v2
	s_nop 0
	v_add_f32_e32 v2, 1.0, v2
	v_rcp_f32_e32 v2, v2
	s_nop 0
	v_mul_f32_e32 v1, v2, v1
	v_mul_f32_e32 v0, v0, v1
	v_cvt_pk_bf16_f32 v0, v0, s0
	ds_write_b16 v138, v0 offset:12480
	v_mul_f32_e32 v0, v25, v25
	v_mul_f32_e32 v1, v41, v41
	v_fmac_f32_e32 v0, v9, v9
	v_fmac_f32_e32 v1, v57, v57
	v_add_f32_e32 v0, v0, v1
	ds_read_u16 v144, v138 offset:4352
	ds_read_u16 v145, v138 offset:4416
	ds_read_u16 v146, v138 offset:4480
	ds_read_u16 v147, v138 offset:4544
	s_nop 1
	v_add_f32_dpp v0, v0, v0 quad_perm:[1,0,3,2] row_mask:0xf bank_mask:0xf
	s_nop 1
	v_add_f32_dpp v0, v0, v0 quad_perm:[2,3,0,1] row_mask:0xf bank_mask:0xf
	s_nop 1
	v_add_f32_dpp v0, v0, v0 row_half_mirror row_mask:0xf bank_mask:0xf
	s_nop 1
	v_add_f32_dpp v0, v0, v0 row_mirror row_mask:0xf bank_mask:0xf
	s_waitcnt lgkmcnt(0)
	ds_bpermute_b32 v1, v137, v0
	s_waitcnt lgkmcnt(0)
	v_add_f32_e32 v0, v0, v1
	v_fmamk_f32 v0, v0, 0x3c000000, v199
	v_rsq_f32_e32 v0, v0
	v_lshlrev_b32_e32 v1, 16, v144
	v_mul_f32_e32 v3, 0xbfb8aa3b, v1
	v_exp_f32_e32 v3, v3
	v_mul_f32_e32 v2, v9, v0
	v_mul_f32_e32 v2, v113, v2
	v_add_f32_e32 v3, 1.0, v3
	v_rcp_f32_e32 v3, v3
	s_nop 0
	v_mul_f32_e32 v1, v3, v1
	v_mul_f32_e32 v1, v2, v1
	v_cvt_pk_bf16_f32 v1, v1, s0
	ds_write_b16 v138, v1 offset:12544
	v_mul_f32_e32 v2, v25, v0
	v_mul_f32_e32 v2, v130, v2
	v_lshlrev_b32_e32 v1, 16, v145
	v_mul_f32_e32 v3, 0xbfb8aa3b, v1
	v_exp_f32_e32 v3, v3
	s_nop 0
	v_add_f32_e32 v3, 1.0, v3
	v_rcp_f32_e32 v3, v3
	s_nop 0
	v_mul_f32_e32 v1, v3, v1
	v_mul_f32_e32 v1, v2, v1
	v_cvt_pk_bf16_f32 v1, v1, s0
	ds_write_b16 v138, v1 offset:12608
	v_mul_f32_e32 v2, v57, v0
	v_mul_f32_e32 v2, v131, v2
	v_mul_f32_e32 v0, v41, v0
	v_mul_f32_e32 v0, v132, v0
	v_lshlrev_b32_e32 v1, 16, v146
	v_mul_f32_e32 v3, 0xbfb8aa3b, v1
	v_exp_f32_e32 v3, v3
	s_nop 0
	v_add_f32_e32 v3, 1.0, v3
	v_rcp_f32_e32 v3, v3
	s_nop 0
	v_mul_f32_e32 v1, v3, v1
	v_mul_f32_e32 v1, v2, v1
	v_cvt_pk_bf16_f32 v1, v1, s0
	ds_write_b16 v138, v1 offset:12672
	v_lshlrev_b32_e32 v1, 16, v147
	v_mul_f32_e32 v2, 0xbfb8aa3b, v1
	v_exp_f32_e32 v2, v2
	s_nop 0
	v_add_f32_e32 v2, 1.0, v2
	v_rcp_f32_e32 v2, v2
	s_nop 0
	v_mul_f32_e32 v1, v2, v1
	v_mul_f32_e32 v0, v0, v1
	v_cvt_pk_bf16_f32 v0, v0, s0
	ds_write_b16 v138, v0 offset:12736
	v_mul_f32_e32 v0, v26, v26
	v_mul_f32_e32 v1, v42, v42
	v_fmac_f32_e32 v0, v10, v10
	v_fmac_f32_e32 v1, v58, v58
	v_add_f32_e32 v0, v0, v1
	ds_read_u16 v144, v138 offset:4608
	ds_read_u16 v145, v138 offset:4672
	ds_read_u16 v146, v138 offset:4736
	ds_read_u16 v147, v138 offset:4800
	s_nop 1
	v_add_f32_dpp v0, v0, v0 quad_perm:[1,0,3,2] row_mask:0xf bank_mask:0xf
	s_nop 1
	v_add_f32_dpp v0, v0, v0 quad_perm:[2,3,0,1] row_mask:0xf bank_mask:0xf
	s_nop 1
	v_add_f32_dpp v0, v0, v0 row_half_mirror row_mask:0xf bank_mask:0xf
	s_nop 1
	v_add_f32_dpp v0, v0, v0 row_mirror row_mask:0xf bank_mask:0xf
	s_waitcnt lgkmcnt(0)
	ds_bpermute_b32 v1, v137, v0
	s_waitcnt lgkmcnt(0)
	v_add_f32_e32 v0, v0, v1
	v_fmamk_f32 v0, v0, 0x3c000000, v199
	v_rsq_f32_e32 v0, v0
	v_lshlrev_b32_e32 v1, 16, v144
	v_mul_f32_e32 v3, 0xbfb8aa3b, v1
	v_exp_f32_e32 v3, v3
	v_mul_f32_e32 v2, v10, v0
	v_mul_f32_e32 v2, v113, v2
	v_add_f32_e32 v3, 1.0, v3
	v_rcp_f32_e32 v3, v3
	s_nop 0
	v_mul_f32_e32 v1, v3, v1
	v_mul_f32_e32 v1, v2, v1
	v_cvt_pk_bf16_f32 v1, v1, s0
	ds_write_b16 v138, v1 offset:12800
	v_mul_f32_e32 v2, v26, v0
	v_mul_f32_e32 v2, v130, v2
	v_lshlrev_b32_e32 v1, 16, v145
	v_mul_f32_e32 v3, 0xbfb8aa3b, v1
	v_exp_f32_e32 v3, v3
	s_nop 0
	v_add_f32_e32 v3, 1.0, v3
	v_rcp_f32_e32 v3, v3
	s_nop 0
	v_mul_f32_e32 v1, v3, v1
	v_mul_f32_e32 v1, v2, v1
	v_cvt_pk_bf16_f32 v1, v1, s0
	ds_write_b16 v138, v1 offset:12864
	v_mul_f32_e32 v2, v58, v0
	v_mul_f32_e32 v2, v131, v2
	v_mul_f32_e32 v0, v42, v0
	v_mul_f32_e32 v0, v132, v0
	v_lshlrev_b32_e32 v1, 16, v146
	v_mul_f32_e32 v3, 0xbfb8aa3b, v1
	v_exp_f32_e32 v3, v3
	s_nop 0
	v_add_f32_e32 v3, 1.0, v3
	v_rcp_f32_e32 v3, v3
	s_nop 0
	v_mul_f32_e32 v1, v3, v1
	v_mul_f32_e32 v1, v2, v1
	v_cvt_pk_bf16_f32 v1, v1, s0
	ds_write_b16 v138, v1 offset:12928
	v_lshlrev_b32_e32 v1, 16, v147
	v_mul_f32_e32 v2, 0xbfb8aa3b, v1
	v_exp_f32_e32 v2, v2
	s_nop 0
	v_add_f32_e32 v2, 1.0, v2
	v_rcp_f32_e32 v2, v2
	s_nop 0
	v_mul_f32_e32 v1, v2, v1
	v_mul_f32_e32 v0, v0, v1
	v_cvt_pk_bf16_f32 v0, v0, s0
	ds_write_b16 v138, v0 offset:12992
	v_mul_f32_e32 v0, v27, v27
	v_mul_f32_e32 v1, v43, v43
	v_fmac_f32_e32 v0, v11, v11
	v_fmac_f32_e32 v1, v59, v59
	v_add_f32_e32 v0, v0, v1
	ds_read_u16 v144, v138 offset:4864
	ds_read_u16 v145, v138 offset:4928
	ds_read_u16 v146, v138 offset:4992
	ds_read_u16 v147, v138 offset:5056
	s_nop 1
	v_add_f32_dpp v0, v0, v0 quad_perm:[1,0,3,2] row_mask:0xf bank_mask:0xf
	s_nop 1
	v_add_f32_dpp v0, v0, v0 quad_perm:[2,3,0,1] row_mask:0xf bank_mask:0xf
	s_nop 1
	v_add_f32_dpp v0, v0, v0 row_half_mirror row_mask:0xf bank_mask:0xf
	s_nop 1
	v_add_f32_dpp v0, v0, v0 row_mirror row_mask:0xf bank_mask:0xf
	s_waitcnt lgkmcnt(0)
; __device__ __forceinline__ int crow(int r, int hi) { return (r & 3) + 8 * (r >> 2) + 4 * hi; }
; __device__ __forceinline__ float bf2f(unsigned short v) { return __uint_as_float((unsigned)v << 16); }
; __device__ __forceinline__ unsigned f2bf(float f) { return pk2(f, 0.f) & 0xffffu; }
; __device__ __forceinline__ int crow(int r, int hi) { return (r & 3) + 8 * (r >> 2) + 4 * hi; }
; __device__ __forceinline__ void gla_pass_c(LAS unsigned char* ldsl, const bf16_t* __restrict__ proj, const float* __restrict__ Btab, const float* __restrict__ Gst, const float* __restrict__ gout, bf16_t* __restrict__ mixed) {
;     ...
;         for (int i = 0; i < 16; ++i) { const int tr = crow(i, hh);
;             const float tot = half_sum32((o[0][i] * o[0][i] + o[1][i] * o[1][i]) + (o[2][i] * o[2][i] + o[3][i] * o[3][i]));
;             const float rr = __builtin_amdgcn_rsqf(tot * (1.0f / 128.0f) + EPS);
; #pragma unroll
;             for (int dvb = 0; dvb < 4; ++dvb) { const float g = bf2f(Lh[tr * 128 + 32 * dvb + r]);
;                 const float val = o[dvb][i] * rr * gn[dvb] * (g * __builtin_amdgcn_rcpf(1.0f + __expf(-g)));
;                 Lh[(32 + tr) * 128 + 32 * dvb + r] = (bf16_t)f2bf(val); } }
	ds_bpermute_b32 v1, v137, v0
	s_waitcnt lgkmcnt(0)
	v_add_f32_e32 v0, v0, v1
	v_fmamk_f32 v0, v0, 0x3c000000, v199
	v_rsq_f32_e32 v0, v0
	v_lshlrev_b32_e32 v1, 16, v144
	v_mul_f32_e32 v3, 0xbfb8aa3b, v1
	v_exp_f32_e32 v3, v3
	v_mul_f32_e32 v2, v11, v0
	v_mul_f32_e32 v2, v113, v2
	v_add_f32_e32 v3, 1.0, v3
	v_rcp_f32_e32 v3, v3
	s_nop 0
	v_mul_f32_e32 v1, v3, v1
	v_mul_f32_e32 v1, v2, v1
	v_cvt_pk_bf16_f32 v1, v1, s0
	ds_write_b16 v138, v1 offset:13056
	v_mul_f32_e32 v2, v27, v0
	v_mul_f32_e32 v2, v130, v2
	v_lshlrev_b32_e32 v1, 16, v145
	v_mul_f32_e32 v3, 0xbfb8aa3b, v1
	v_exp_f32_e32 v3, v3
	s_nop 0
	v_add_f32_e32 v3, 1.0, v3
	v_rcp_f32_e32 v3, v3
	s_nop 0
	v_mul_f32_e32 v1, v3, v1
	v_mul_f32_e32 v1, v2, v1
	v_cvt_pk_bf16_f32 v1, v1, s0
	ds_write_b16 v138, v1 offset:13120
	v_mul_f32_e32 v2, v59, v0
	v_mul_f32_e32 v2, v131, v2
	v_mul_f32_e32 v0, v43, v0
	v_mul_f32_e32 v0, v132, v0
	v_lshlrev_b32_e32 v1, 16, v146
	v_mul_f32_e32 v3, 0xbfb8aa3b, v1
	v_exp_f32_e32 v3, v3
	s_nop 0
	v_add_f32_e32 v3, 1.0, v3
	v_rcp_f32_e32 v3, v3
	s_nop 0
	v_mul_f32_e32 v1, v3, v1
	v_mul_f32_e32 v1, v2, v1
	v_cvt_pk_bf16_f32 v1, v1, s0
	ds_write_b16 v138, v1 offset:13184
	v_lshlrev_b32_e32 v1, 16, v147
	v_mul_f32_e32 v2, 0xbfb8aa3b, v1
	v_exp_f32_e32 v2, v2
	s_nop 0
	v_add_f32_e32 v2, 1.0, v2
	v_rcp_f32_e32 v2, v2
	s_nop 0
	v_mul_f32_e32 v1, v2, v1
	v_mul_f32_e32 v0, v0, v1
	v_cvt_pk_bf16_f32 v0, v0, s0
	ds_write_b16 v138, v0 offset:13248
	v_mul_f32_e32 v0, v28, v28
	v_mul_f32_e32 v1, v44, v44
	v_fmac_f32_e32 v0, v12, v12
	v_fmac_f32_e32 v1, v60, v60
	v_add_f32_e32 v0, v0, v1
	ds_read_u16 v144, v138 offset:6144
	ds_read_u16 v145, v138 offset:6208
	ds_read_u16 v146, v138 offset:6272
	ds_read_u16 v147, v138 offset:6336
	s_nop 1
	v_add_f32_dpp v0, v0, v0 quad_perm:[1,0,3,2] row_mask:0xf bank_mask:0xf
	s_nop 1
	v_add_f32_dpp v0, v0, v0 quad_perm:[2,3,0,1] row_mask:0xf bank_mask:0xf
	s_nop 1
	v_add_f32_dpp v0, v0, v0 row_half_mirror row_mask:0xf bank_mask:0xf
	s_nop 1
	v_add_f32_dpp v0, v0, v0 row_mirror row_mask:0xf bank_mask:0xf
	s_waitcnt lgkmcnt(0)
	ds_bpermute_b32 v1, v137, v0
	s_waitcnt lgkmcnt(0)
	v_add_f32_e32 v0, v0, v1
	v_fmamk_f32 v0, v0, 0x3c000000, v199
	v_rsq_f32_e32 v0, v0
	v_lshlrev_b32_e32 v1, 16, v144
	v_mul_f32_e32 v3, 0xbfb8aa3b, v1
	v_exp_f32_e32 v3, v3
	v_mul_f32_e32 v2, v12, v0
	v_mul_f32_e32 v2, v113, v2
	v_add_f32_e32 v3, 1.0, v3
	v_rcp_f32_e32 v3, v3
	s_nop 0
	v_mul_f32_e32 v1, v3, v1
	v_mul_f32_e32 v1, v2, v1
	v_cvt_pk_bf16_f32 v1, v1, s0
	ds_write_b16 v138, v1 offset:14336
	v_mul_f32_e32 v2, v28, v0
	v_mul_f32_e32 v2, v130, v2
	v_lshlrev_b32_e32 v1, 16, v145
	v_mul_f32_e32 v3, 0xbfb8aa3b, v1
	v_exp_f32_e32 v3, v3
	s_nop 0
	v_add_f32_e32 v3, 1.0, v3
	v_rcp_f32_e32 v3, v3
	s_nop 0
	v_mul_f32_e32 v1, v3, v1
	v_mul_f32_e32 v1, v2, v1
	v_cvt_pk_bf16_f32 v1, v1, s0
	ds_write_b16 v138, v1 offset:14400
	v_mul_f32_e32 v2, v60, v0
	v_mul_f32_e32 v2, v131, v2
	v_mul_f32_e32 v0, v44, v0
	v_mul_f32_e32 v0, v132, v0
	v_lshlrev_b32_e32 v1, 16, v146
	v_mul_f32_e32 v3, 0xbfb8aa3b, v1
	v_exp_f32_e32 v3, v3
	s_nop 0
	v_add_f32_e32 v3, 1.0, v3
	v_rcp_f32_e32 v3, v3
	s_nop 0
	v_mul_f32_e32 v1, v3, v1
	v_mul_f32_e32 v1, v2, v1
	v_cvt_pk_bf16_f32 v1, v1, s0
	ds_write_b16 v138, v1 offset:14464
	v_lshlrev_b32_e32 v1, 16, v147
	v_mul_f32_e32 v2, 0xbfb8aa3b, v1
	v_exp_f32_e32 v2, v2
	s_nop 0
	v_add_f32_e32 v2, 1.0, v2
	v_rcp_f32_e32 v2, v2
	s_nop 0
	v_mul_f32_e32 v1, v2, v1
	v_mul_f32_e32 v0, v0, v1
	v_cvt_pk_bf16_f32 v0, v0, s0
	ds_write_b16 v138, v0 offset:14528
	v_mul_f32_e32 v0, v29, v29
	v_mul_f32_e32 v1, v45, v45
	v_fmac_f32_e32 v0, v13, v13
	v_fmac_f32_e32 v1, v61, v61
	v_add_f32_e32 v0, v0, v1
	ds_read_u16 v144, v138 offset:6400
	ds_read_u16 v145, v138 offset:6464
	ds_read_u16 v146, v138 offset:6528
	ds_read_u16 v147, v138 offset:6592
	s_nop 1
	v_add_f32_dpp v0, v0, v0 quad_perm:[1,0,3,2] row_mask:0xf bank_mask:0xf
	s_nop 1
	v_add_f32_dpp v0, v0, v0 quad_perm:[2,3,0,1] row_mask:0xf bank_mask:0xf
	s_nop 1
	v_add_f32_dpp v0, v0, v0 row_half_mirror row_mask:0xf bank_mask:0xf
	s_nop 1
	v_add_f32_dpp v0, v0, v0 row_mirror row_mask:0xf bank_mask:0xf
	s_waitcnt lgkmcnt(0)
	ds_bpermute_b32 v1, v137, v0
	s_waitcnt lgkmcnt(0)
	v_add_f32_e32 v0, v0, v1
	v_fmamk_f32 v0, v0, 0x3c000000, v199
	v_rsq_f32_e32 v0, v0
	v_lshlrev_b32_e32 v1, 16, v144
	v_mul_f32_e32 v3, 0xbfb8aa3b, v1
	v_exp_f32_e32 v3, v3
	v_mul_f32_e32 v2, v13, v0
	v_mul_f32_e32 v2, v113, v2
	v_add_f32_e32 v3, 1.0, v3
	v_rcp_f32_e32 v3, v3
	s_nop 0
	v_mul_f32_e32 v1, v3, v1
	v_mul_f32_e32 v1, v2, v1
	v_cvt_pk_bf16_f32 v1, v1, s0
	ds_write_b16 v138, v1 offset:14592
	v_mul_f32_e32 v2, v29, v0
	v_mul_f32_e32 v2, v130, v2
	v_lshlrev_b32_e32 v1, 16, v145
	v_mul_f32_e32 v3, 0xbfb8aa3b, v1
	v_exp_f32_e32 v3, v3
	s_nop 0
	v_add_f32_e32 v3, 1.0, v3
	v_rcp_f32_e32 v3, v3
	s_nop 0
	v_mul_f32_e32 v1, v3, v1
	v_mul_f32_e32 v1, v2, v1
	v_cvt_pk_bf16_f32 v1, v1, s0
	ds_write_b16 v138, v1 offset:14656
	v_mul_f32_e32 v2, v61, v0
	v_mul_f32_e32 v2, v131, v2
	v_mul_f32_e32 v0, v45, v0
	v_mul_f32_e32 v0, v132, v0
	v_lshlrev_b32_e32 v1, 16, v146
	v_mul_f32_e32 v3, 0xbfb8aa3b, v1
	v_exp_f32_e32 v3, v3
	s_nop 0
	v_add_f32_e32 v3, 1.0, v3
	v_rcp_f32_e32 v3, v3
	s_nop 0
	v_mul_f32_e32 v1, v3, v1
	v_mul_f32_e32 v1, v2, v1
	v_cvt_pk_bf16_f32 v1, v1, s0
	ds_write_b16 v138, v1 offset:14720
	v_lshlrev_b32_e32 v1, 16, v147
	v_mul_f32_e32 v2, 0xbfb8aa3b, v1
	v_exp_f32_e32 v2, v2
	s_nop 0
	v_add_f32_e32 v2, 1.0, v2
	v_rcp_f32_e32 v2, v2
	s_nop 0
	v_mul_f32_e32 v1, v2, v1
	v_mul_f32_e32 v0, v0, v1
	v_cvt_pk_bf16_f32 v0, v0, s0
	ds_write_b16 v138, v0 offset:14784
	v_mul_f32_e32 v0, v30, v30
	v_mul_f32_e32 v1, v46, v46
	v_fmac_f32_e32 v0, v14, v14
	v_fmac_f32_e32 v1, v62, v62
	v_add_f32_e32 v0, v0, v1
	ds_read_u16 v144, v138 offset:6656
	ds_read_u16 v145, v138 offset:6720
	ds_read_u16 v146, v138 offset:6784
	ds_read_u16 v147, v138 offset:6848
	s_nop 1
	v_add_f32_dpp v0, v0, v0 quad_perm:[1,0,3,2] row_mask:0xf bank_mask:0xf
	s_nop 1
	v_add_f32_dpp v0, v0, v0 quad_perm:[2,3,0,1] row_mask:0xf bank_mask:0xf
	s_nop 1
	v_add_f32_dpp v0, v0, v0 row_half_mirror row_mask:0xf bank_mask:0xf
	s_nop 1
	v_add_f32_dpp v0, v0, v0 row_mirror row_mask:0xf bank_mask:0xf
	s_waitcnt lgkmcnt(0)
; #define LAS __attribute__((address_space(3)))
; __device__ __forceinline__ int crow(int r, int hi) { return (r & 3) + 8 * (r >> 2) + 4 * hi; }
; __device__ __forceinline__ float bf2f(unsigned short v) { return __uint_as_float((unsigned)v << 16); }
; __device__ __forceinline__ unsigned f2bf(float f) { return pk2(f, 0.f) & 0xffffu; }
; __device__ __forceinline__ int crow(int r, int hi) { return (r & 3) + 8 * (r >> 2) + 4 * hi; }
; __device__ __forceinline__ void gla_pass_c(LAS unsigned char* ldsl, const bf16_t* __restrict__ proj, const float* __restrict__ Btab, const float* __restrict__ Gst, const float* __restrict__ gout, bf16_t* __restrict__ mixed) {
;     ...
;         for (int i = 0; i < 16; ++i) { const int tr = crow(i, hh);
;             const float tot = half_sum32((o[0][i] * o[0][i] + o[1][i] * o[1][i]) + (o[2][i] * o[2][i] + o[3][i] * o[3][i]));
;             const float rr = __builtin_amdgcn_rsqf(tot * (1.0f / 128.0f) + EPS);
; #pragma unroll
;             for (int dvb = 0; dvb < 4; ++dvb) { const float g = bf2f(Lh[tr * 128 + 32 * dvb + r]);
;                 const float val = o[dvb][i] * rr * gn[dvb] * (g * __builtin_amdgcn_rcpf(1.0f + __expf(-g)));
;                 Lh[(32 + tr) * 128 + 32 * dvb + r] = (bf16_t)f2bf(val); } }
;         { bf16_t* mp = mixed + (row0 + 32 * tb + crw) * DM + h * 128 + ccl * 8;
; #pragma unroll
;           for (int i = 0; i < 8; ++i) *(u32x4*)(mp + (size_t)(4 * i) * DM) = *(const LAS u32x4*)(Lw + (32 + 4 * i + crw) * 256 + ccl * 16); }
	ds_bpermute_b32 v1, v137, v0
	s_waitcnt lgkmcnt(0)
	v_add_f32_e32 v0, v0, v1
	v_fmamk_f32 v0, v0, 0x3c000000, v199
	v_rsq_f32_e32 v0, v0
	v_lshlrev_b32_e32 v1, 16, v144
	v_mul_f32_e32 v3, 0xbfb8aa3b, v1
	v_exp_f32_e32 v3, v3
	v_mul_f32_e32 v2, v14, v0
	v_mul_f32_e32 v2, v113, v2
	v_add_f32_e32 v3, 1.0, v3
	v_rcp_f32_e32 v3, v3
	s_nop 0
	v_mul_f32_e32 v1, v3, v1
	v_mul_f32_e32 v1, v2, v1
	v_cvt_pk_bf16_f32 v1, v1, s0
	ds_write_b16 v138, v1 offset:14848
	v_mul_f32_e32 v2, v30, v0
	v_mul_f32_e32 v2, v130, v2
	v_lshlrev_b32_e32 v1, 16, v145
	v_mul_f32_e32 v3, 0xbfb8aa3b, v1
	v_exp_f32_e32 v3, v3
	s_nop 0
	v_add_f32_e32 v3, 1.0, v3
	v_rcp_f32_e32 v3, v3
	s_nop 0
	v_mul_f32_e32 v1, v3, v1
	v_mul_f32_e32 v1, v2, v1
	v_cvt_pk_bf16_f32 v1, v1, s0
	ds_write_b16 v138, v1 offset:14912
	v_mul_f32_e32 v2, v62, v0
	v_mul_f32_e32 v2, v131, v2
	v_mul_f32_e32 v0, v46, v0
	v_mul_f32_e32 v0, v132, v0
	v_lshlrev_b32_e32 v1, 16, v146
	v_mul_f32_e32 v3, 0xbfb8aa3b, v1
	v_exp_f32_e32 v3, v3
	s_nop 0
	v_add_f32_e32 v3, 1.0, v3
	v_rcp_f32_e32 v3, v3
	s_nop 0
	v_mul_f32_e32 v1, v3, v1
	v_mul_f32_e32 v1, v2, v1
	v_cvt_pk_bf16_f32 v1, v1, s0
	ds_write_b16 v138, v1 offset:14976
	v_lshlrev_b32_e32 v1, 16, v147
	v_mul_f32_e32 v2, 0xbfb8aa3b, v1
	v_exp_f32_e32 v2, v2
	s_nop 0
	v_add_f32_e32 v2, 1.0, v2
	v_rcp_f32_e32 v2, v2
	s_nop 0
	v_mul_f32_e32 v1, v2, v1
	v_mul_f32_e32 v0, v0, v1
	v_cvt_pk_bf16_f32 v0, v0, s0
	ds_write_b16 v138, v0 offset:15040
	v_mul_f32_e32 v0, v31, v31
	v_mul_f32_e32 v1, v47, v47
	v_fmac_f32_e32 v0, v15, v15
	v_fmac_f32_e32 v1, v63, v63
	v_add_f32_e32 v0, v0, v1
	ds_read_u16 v144, v138 offset:6912
	ds_read_u16 v145, v138 offset:6976
	ds_read_u16 v146, v138 offset:7040
	ds_read_u16 v147, v138 offset:7104
	s_nop 1
	v_add_f32_dpp v0, v0, v0 quad_perm:[1,0,3,2] row_mask:0xf bank_mask:0xf
	s_nop 1
	v_add_f32_dpp v0, v0, v0 quad_perm:[2,3,0,1] row_mask:0xf bank_mask:0xf
	s_nop 1
	v_add_f32_dpp v0, v0, v0 row_half_mirror row_mask:0xf bank_mask:0xf
	s_nop 1
	v_add_f32_dpp v0, v0, v0 row_mirror row_mask:0xf bank_mask:0xf
	s_waitcnt lgkmcnt(0)
	ds_bpermute_b32 v1, v137, v0
	s_waitcnt lgkmcnt(0)
	v_add_f32_e32 v0, v0, v1
	v_fmamk_f32 v0, v0, 0x3c000000, v199
	v_rsq_f32_e32 v0, v0
	v_lshlrev_b32_e32 v1, 16, v144
	v_mul_f32_e32 v3, 0xbfb8aa3b, v1
	v_exp_f32_e32 v3, v3
	v_mul_f32_e32 v2, v15, v0
	v_mul_f32_e32 v2, v113, v2
	v_add_f32_e32 v3, 1.0, v3
	v_rcp_f32_e32 v3, v3
	s_nop 0
	v_mul_f32_e32 v1, v3, v1
	v_mul_f32_e32 v1, v2, v1
	v_cvt_pk_bf16_f32 v1, v1, s0
	ds_write_b16 v138, v1 offset:15104
	v_mul_f32_e32 v2, v31, v0
	v_mul_f32_e32 v2, v130, v2
	v_lshlrev_b32_e32 v1, 16, v145
	v_mul_f32_e32 v3, 0xbfb8aa3b, v1
	v_exp_f32_e32 v3, v3
	s_nop 0
	v_add_f32_e32 v3, 1.0, v3
	v_rcp_f32_e32 v3, v3
	s_nop 0
	v_mul_f32_e32 v1, v3, v1
	v_mul_f32_e32 v1, v2, v1
	v_cvt_pk_bf16_f32 v1, v1, s0
	ds_write_b16 v138, v1 offset:15168
	v_mul_f32_e32 v2, v63, v0
	v_mul_f32_e32 v2, v131, v2
	v_mul_f32_e32 v0, v47, v0
	v_mul_f32_e32 v0, v132, v0
	v_lshlrev_b32_e32 v1, 16, v146
	v_mul_f32_e32 v3, 0xbfb8aa3b, v1
	v_exp_f32_e32 v3, v3
	s_nop 0
	v_add_f32_e32 v3, 1.0, v3
	v_rcp_f32_e32 v3, v3
	s_nop 0
	v_mul_f32_e32 v1, v3, v1
	v_mul_f32_e32 v1, v2, v1
	v_cvt_pk_bf16_f32 v1, v1, s0
	ds_write_b16 v138, v1 offset:15232
	v_lshlrev_b32_e32 v1, 16, v147
	v_mul_f32_e32 v2, 0xbfb8aa3b, v1
	v_exp_f32_e32 v2, v2
	s_nop 0
	v_add_f32_e32 v2, 1.0, v2
	v_rcp_f32_e32 v2, v2
	s_nop 0
	v_mul_f32_e32 v1, v2, v1
	v_mul_f32_e32 v0, v0, v1
	v_cvt_pk_bf16_f32 v0, v0, s0
	ds_write_b16 v138, v0 offset:15296
	v_lshlrev_b64 v[0:1], 11, v[122:123]
	v_lshl_add_u64 v[0:1], s[54:55], 0, v[0:1]
	v_lshl_add_u64 v[0:1], v[0:1], 0, v[160:161]
	v_lshl_add_u64 v[4:5], v[0:1], 0, v[120:121]
	ds_read_b128 v[0:3], v140 offset:8192
	v_add_co_u32_e32 v6, vcc, s2, v4
	s_movk_i32 s2, 0x6000
	s_nop 0
	v_addc_co_u32_e32 v7, vcc, 0, v5, vcc
	s_waitcnt lgkmcnt(0)
	global_store_dwordx4 v[4:5], v[0:3], off
	ds_read_b128 v[0:3], v140 offset:9216
	s_waitcnt lgkmcnt(0)
	global_store_dwordx4 v[6:7], v[0:3], off
	ds_read_b128 v[0:3], v140 offset:10240
	v_add_co_u32_e32 v6, vcc, s49, v4
	s_nop 1
	v_addc_co_u32_e32 v7, vcc, 0, v5, vcc
	s_waitcnt lgkmcnt(0)
	global_store_dwordx4 v[6:7], v[0:3], off
	ds_read_b128 v[0:3], v140 offset:11264
	v_add_co_u32_e32 v6, vcc, s2, v4
	s_mov_b32 s2, 0xa000
	s_nop 0
	v_addc_co_u32_e32 v7, vcc, 0, v5, vcc
	s_waitcnt lgkmcnt(0)
	global_store_dwordx4 v[6:7], v[0:3], off
	ds_read_b128 v[0:3], v140 offset:12288
	v_add_co_u32_e32 v6, vcc, s42, v4
	s_nop 1
	v_addc_co_u32_e32 v7, vcc, 0, v5, vcc
	s_waitcnt lgkmcnt(0)
	global_store_dwordx4 v[6:7], v[0:3], off
	ds_read_b128 v[0:3], v140 offset:13312
	v_add_co_u32_e32 v6, vcc, s2, v4
	s_movk_i32 s2, 0x7ff
	s_nop 0
	v_addc_co_u32_e32 v7, vcc, 0, v5, vcc
	s_waitcnt lgkmcnt(0)
	global_store_dwordx4 v[6:7], v[0:3], off
	ds_read_b128 v[0:3], v140 offset:14336
	v_add_co_u32_e32 v6, vcc, 0xc000, v4
	s_nop 1
	v_addc_co_u32_e32 v7, vcc, 0, v5, vcc
	s_waitcnt lgkmcnt(0)
	global_store_dwordx4 v[6:7], v[0:3], off
	ds_read_b128 v[0:3], v140 offset:15360
	v_add_co_u32_e32 v4, vcc, 0xe000, v4
	s_nop 1
	v_addc_co_u32_e32 v5, vcc, 0, v5, vcc
	s_waitcnt lgkmcnt(0)
	global_store_dwordx4 v[4:5], v[0:3], off
	v_cmp_lt_i32_e32 vcc, s2, v111
	s_or_b64 s[40:41], vcc, s[40:41]
	v_add_u32_e32 v0, 0x800, v111
	v_mov_b32_e32 v111, v0
	s_andn2_b64 exec, exec, s[40:41]
	s_cbranch_execz .LBB0_880
; #define LAS __attribute__((address_space(3)))
; __device__ __forceinline__ void gla_pass_c(LAS unsigned char* ldsl, const bf16_t* __restrict__ proj, const float* __restrict__ Btab, const float* __restrict__ Gst, const float* __restrict__ gout, bf16_t* __restrict__ mixed) {
;     ...
;     for (int u = gw; u < 16 * 128 * 2; u += NGW) { const int item = u >> 1, tb = __builtin_amdgcn_readfirstlane((u ^ (u >> 11) ^ (u >> 3)) & 1);
;         const int bh = item >> 7, n = item & 127, b = bh >> 2, h = bh & 3; const size_t row0 = (size_t)b * SEQ + (size_t)n * 64;
;         const int tl = 32 * tb + r;
;         { const bf16_t* vp = proj + (row0 + crw) * NIN + 512 + h * 128 + ccl * 8; u32x4 sv[8];
; #pragma unroll
;           for (int i = 0; i < 8; ++i) sv[i] = *(const u32x4*)(vp + (size_t)(4 * i) * NIN);
; #pragma unroll
;           for (int i = 0; i < 8; ++i) *(LAS u32x4*)(Lw + (4 * i + crw) * 256 + ccl * 16) = sv[i];
;           if (tb) {
; #pragma unroll
;               for (int i = 0; i < 8; ++i) sv[i] = *(const u32x4*)(vp + (size_t)(32 + 4 * i) * NIN);
; #pragma unroll
;               for (int i = 0; i < 8; ++i) *(LAS u32x4*)(Lw + (32 + 4 * i + crw) * 256 + ccl * 16) = sv[i]; } }
;     ...
;         { const bf16_t* gp = proj + (row0 + 32 * tb + crw) * NIN + 1024 + h * 128 + ccl * 8; u32x4 sv[8];
; #pragma unroll
;           for (int i = 0; i < 8; ++i) sv[i] = *(const u32x4*)(gp + (size_t)(4 * i) * NIN);
.LBB0_874:
	v_ashrrev_i32_e32 v2, 10, v111
	v_ashrrev_i32_e32 v0, 1, v111
	v_ashrrev_i32_e32 v3, 31, v2
	v_lshlrev_b64 v[64:65], 13, v[2:3]
	v_lshlrev_b32_e32 v2, 6, v0
	v_and_b32_e32 v66, 0x1fc0, v2
	v_or_b32_e32 v122, v64, v66
	v_or_b32_e32 v2, v122, v110
	v_mov_b32_e32 v3, v65
	v_bfe_u32 v1, v111, 8, 2
	v_lshlrev_b64 v[2:3], 12, v[2:3]
	v_lshl_add_u64 v[2:3], s[60:61], 0, v[2:3]
	v_lshlrev_b32_e32 v160, 8, v1
	v_lshl_add_u64 v[2:3], v[2:3], 0, v[160:161]
	v_mov_b32_e32 v121, v161
	v_lshl_add_u64 v[2:3], v[2:3], 0, v[120:121]
	v_add_co_u32_e32 v8, vcc, s49, v2
	s_mov_b32 s2, 0xc000
	s_nop 0
	v_addc_co_u32_e32 v9, vcc, 0, v3, vcc
	v_add_co_u32_e32 v12, vcc, s42, v2
	global_load_dwordx4 v[4:7], v[2:3], off offset:1024
	s_nop 0
	global_load_dwordx4 v[8:11], v[8:9], off offset:1024
	v_addc_co_u32_e32 v13, vcc, 0, v3, vcc
	v_add_co_u32_e32 v16, vcc, s2, v2
	v_lshrrev_b32_e32 v36, 11, v111
	s_nop 0
	v_addc_co_u32_e32 v17, vcc, 0, v3, vcc
	v_add_co_u32_e32 v20, vcc, s51, v2
	global_load_dwordx4 v[12:15], v[12:13], off offset:1024
	s_nop 0
	global_load_dwordx4 v[16:19], v[16:17], off offset:1024
	v_addc_co_u32_e32 v21, vcc, 0, v3, vcc
	v_add_co_u32_e32 v24, vcc, s52, v2
	v_lshrrev_b32_e32 v37, 3, v111
	s_nop 0
	v_addc_co_u32_e32 v25, vcc, 0, v3, vcc
	v_add_co_u32_e32 v28, vcc, s33, v2
	global_load_dwordx4 v[20:23], v[20:21], off offset:1024
	s_nop 0
	global_load_dwordx4 v[24:27], v[24:25], off offset:1024
	v_addc_co_u32_e32 v29, vcc, 0, v3, vcc
	v_add_co_u32_e32 v32, vcc, 0x1c000, v2
	global_load_dwordx4 v[28:31], v[28:29], off offset:1024
	s_nop 0
	v_addc_co_u32_e32 v33, vcc, 0, v3, vcc
	global_load_dwordx4 v[32:35], v[32:33], off offset:1024
	v_xor_b32_e32 v36, v36, v37
	v_xor_b32_e32 v36, v36, v111
	v_mov_b32_e32 v123, v65
	v_readfirstlane_b32 s2, v36
	s_and_b32 s3, s2, 1
	s_lshl_b32 s46, s3, 17
	s_mov_b32 s47, 0
	v_lshl_add_u64 v[238:239], v[2:3], 0, s[46:47]
	global_load_dwordx4 v[206:209], v[238:239], off offset:2048
	v_add_co_u32_e32 v238, vcc, 0x4000, v238
	s_nop 1
	v_addc_co_u32_e32 v239, vcc, 0, v239, vcc
	global_load_dwordx4 v[210:213], v[238:239], off offset:2048
	v_add_co_u32_e32 v238, vcc, 0x4000, v238
	s_nop 1
	v_addc_co_u32_e32 v239, vcc, 0, v239, vcc
	global_load_dwordx4 v[214:217], v[238:239], off offset:2048
	v_add_co_u32_e32 v238, vcc, 0x4000, v238
	s_nop 1
	v_addc_co_u32_e32 v239, vcc, 0, v239, vcc
	global_load_dwordx4 v[218:221], v[238:239], off offset:2048
	v_add_co_u32_e32 v238, vcc, 0x4000, v238
	s_nop 1
	v_addc_co_u32_e32 v239, vcc, 0, v239, vcc
	global_load_dwordx4 v[222:225], v[238:239], off offset:2048
	v_add_co_u32_e32 v238, vcc, 0x4000, v238
	s_nop 1
	v_addc_co_u32_e32 v239, vcc, 0, v239, vcc
	global_load_dwordx4 v[226:229], v[238:239], off offset:2048
	v_add_co_u32_e32 v238, vcc, 0x4000, v238
	s_nop 1
	v_addc_co_u32_e32 v239, vcc, 0, v239, vcc
	global_load_dwordx4 v[230:233], v[238:239], off offset:2048
	v_add_co_u32_e32 v238, vcc, 0x4000, v238
	s_nop 1
	v_addc_co_u32_e32 v239, vcc, 0, v239, vcc
	global_load_dwordx4 v[234:237], v[238:239], off offset:2048
	s_cmp_eq_u32 s3, 0
	s_waitcnt vmcnt(15)
	ds_write_b128 v140, v[4:7]
	s_waitcnt vmcnt(14)
	ds_write_b128 v140, v[8:11] offset:1024
	s_waitcnt vmcnt(13)
	ds_write_b128 v140, v[12:15] offset:2048
	s_waitcnt vmcnt(12)
	ds_write_b128 v140, v[16:19] offset:3072
	s_waitcnt vmcnt(11)
	ds_write_b128 v140, v[20:23] offset:4096
	s_waitcnt vmcnt(10)
	ds_write_b128 v140, v[24:27] offset:5120
	s_waitcnt vmcnt(9)
	ds_write_b128 v140, v[28:31] offset:6144
	s_waitcnt vmcnt(8)
	ds_write_b128 v140, v[32:35] offset:7168
	s_cbranch_scc1 .LBB0_876
	s_mov_b64 s[42:43], 0x400
	v_lshl_add_u64 v[26:27], v[2:3], 0, s[42:43]
	v_add_co_u32_e32 v2, vcc, 0x20000, v26
	s_nop 1
	v_addc_co_u32_e32 v3, vcc, 0, v27, vcc
	v_add_co_u32_e32 v6, vcc, 0x24000, v26
	s_nop 1
	v_addc_co_u32_e32 v7, vcc, 0, v27, vcc
	v_add_co_u32_e32 v10, vcc, 0x28000, v26
	global_load_dwordx4 v[2:5], v[2:3], off
	s_nop 0
	global_load_dwordx4 v[6:9], v[6:7], off
	v_addc_co_u32_e32 v11, vcc, 0, v27, vcc
	v_add_co_u32_e32 v14, vcc, 0x2c000, v26
	s_nop 1
	v_addc_co_u32_e32 v15, vcc, 0, v27, vcc
	v_add_co_u32_e32 v18, vcc, 0x30000, v26
	global_load_dwordx4 v[10:13], v[10:11], off
	s_nop 0
	global_load_dwordx4 v[14:17], v[14:15], off
	v_addc_co_u32_e32 v19, vcc, 0, v27, vcc
	v_add_co_u32_e32 v22, vcc, 0x34000, v26
	s_nop 1
	v_addc_co_u32_e32 v23, vcc, 0, v27, vcc
	v_add_co_u32_e32 v28, vcc, 0x38000, v26
	global_load_dwordx4 v[18:21], v[18:19], off
	s_nop 0
	global_load_dwordx4 v[22:25], v[22:23], off
	v_addc_co_u32_e32 v29, vcc, 0, v27, vcc
	v_add_co_u32_e32 v30, vcc, 0x3c000, v26
	s_nop 1
	v_addc_co_u32_e32 v31, vcc, 0, v27, vcc
	global_load_dwordx4 v[26:29], v[28:29], off
	s_nop 0
	global_load_dwordx4 v[30:33], v[30:31], off
	s_waitcnt vmcnt(7)
	ds_write_b128 v140, v[2:5] offset:8192
	s_waitcnt vmcnt(6)
	ds_write_b128 v140, v[6:9] offset:9216
	s_waitcnt vmcnt(5)
	ds_write_b128 v140, v[10:13] offset:10240
	s_waitcnt vmcnt(4)
	ds_write_b128 v140, v[14:17] offset:11264
	s_waitcnt vmcnt(3)
	ds_write_b128 v140, v[18:21] offset:12288
	s_waitcnt vmcnt(2)
	ds_write_b128 v140, v[22:25] offset:13312
	s_waitcnt vmcnt(1)
	ds_write_b128 v140, v[26:29] offset:14336
	s_waitcnt vmcnt(0)
	ds_write_b128 v140, v[30:33] offset:15360
